# differential attention: V^T fragment LDS reads of three sub-tile bodies issued at the head of the exp section into the VGPRs freed by the LDS-DMA staging; PV MFMAs wait with counted lgkmcnt (on v98)
# speedup vs baseline: 1.0077x; 1.0021x over previous
.LBB0_333:
	v_add_u32_e32 v206, v1, v236
	v_add_u32_e32 v207, v1, v237
	ds_read_b128 v[132:135], v206 offset:32768
	ds_read_b128 v[136:139], v207 offset:32768
	ds_read_b128 v[140:143], v206 offset:40960
	ds_read_b128 v[144:147], v207 offset:40960
	ds_read_b128 v[148:151], v206 offset:49152
	ds_read_b128 v[152:155], v207 offset:49152
	ds_read_b128 v[156:159], v206 offset:57344
	ds_read_b128 v[160:163], v207 offset:57344
	v_sub_f32_e32 v6, v246, v6
	v_sub_f32_e32 v7, v80, v6
	v_exp_f32_e32 v7, v7
	v_sub_f32_e32 v9, v81, v6
	v_exp_f32_e32 v9, v9
	v_sub_f32_e32 v10, v82, v6
	v_exp_f32_e32 v10, v10
	v_sub_f32_e32 v11, v83, v6
	v_exp_f32_e32 v11, v11
	v_sub_f32_e32 v12, v84, v6
	v_add_f32_e32 v8, 0, v7
	v_exp_f32_e32 v12, v12
	v_sub_f32_e32 v13, v85, v6
	v_add_f32_e32 v8, v9, v8
	v_exp_f32_e32 v13, v13
	v_sub_f32_e32 v14, v86, v6
	v_add_f32_e32 v8, v10, v8
	v_exp_f32_e32 v14, v14
	v_sub_f32_e32 v15, v87, v6
	v_add_f32_e32 v8, v11, v8
	v_exp_f32_e32 v15, v15
	v_sub_f32_e32 v80, v88, v6
	v_add_f32_e32 v8, v12, v8
	v_exp_f32_e32 v80, v80
	v_sub_f32_e32 v81, v89, v6
	v_add_f32_e32 v8, v13, v8
	v_exp_f32_e32 v81, v81
	v_sub_f32_e32 v82, v90, v6
	v_add_f32_e32 v8, v14, v8
	v_exp_f32_e32 v82, v82
	v_sub_f32_e32 v83, v91, v6
	v_add_f32_e32 v8, v15, v8
	v_exp_f32_e32 v83, v83
	v_add_f32_e32 v8, v80, v8
	v_add_f32_e32 v8, v81, v8
	v_sub_f32_e32 v84, v92, v6
	v_sub_f32_e32 v85, v93, v6
	v_sub_f32_e32 v86, v94, v6
	v_sub_f32_e32 v6, v95, v6
	v_add_f32_e32 v8, v82, v8
	v_exp_f32_e32 v87, v6
	v_cvt_pk_bf16_f32 v6, v7, v9
	v_cvt_pk_bf16_f32 v9, v14, v15
	v_add_f32_e32 v8, v83, v8
	v_cvt_pk_bf16_f32 v7, v10, v11
	v_cvt_pk_bf16_f32 v10, v80, v81
	v_cvt_pk_bf16_f32 v11, v82, v83
	v_exp_f32_e32 v84, v84
	v_exp_f32_e32 v85, v85
	v_exp_f32_e32 v86, v86
	v_add_f32_e32 v8, v84, v8
	v_add_f32_e32 v8, v85, v8
	v_add_f32_e32 v8, v86, v8
	v_add_f32_e32 v88, v87, v8
	v_cvt_pk_bf16_f32 v8, v12, v13
	v_cvt_pk_bf16_f32 v12, v84, v85
	v_cvt_pk_bf16_f32 v13, v86, v87
	s_waitcnt lgkmcnt(7)
	v_mfma_f32_32x32x16_bf16 v[64:79], v[132:135], v[6:9], v[64:79]
	v_add_f32_e32 v245, v245, v88
	s_waitcnt lgkmcnt(6)
	v_mfma_f32_32x32x16_bf16 v[64:79], v[136:139], v[10:13], v[64:79]
	s_waitcnt lgkmcnt(5)
	v_mfma_f32_32x32x16_bf16 v[48:63], v[140:143], v[6:9], v[48:63]
	s_waitcnt lgkmcnt(4)
	v_mfma_f32_32x32x16_bf16 v[48:63], v[144:147], v[10:13], v[48:63]
	s_waitcnt lgkmcnt(3)
	v_mfma_f32_32x32x16_bf16 v[32:47], v[148:151], v[6:9], v[32:47]
	s_waitcnt lgkmcnt(2)
	v_mfma_f32_32x32x16_bf16 v[32:47], v[152:155], v[10:13], v[32:47]
	s_waitcnt lgkmcnt(1)
	v_mfma_f32_32x32x16_bf16 v[16:31], v[156:159], v[6:9], v[16:31]
	s_waitcnt lgkmcnt(0)
	v_mfma_f32_32x32x16_bf16 v[16:31], v[160:163], v[10:13], v[16:31]
	s_add_i32 s8, s59, 2
	s_cmp_gt_u32 s8, s55
	s_cbranch_scc1 .LBB0_307

.LBB0_356:
	v_add_u32_e32 v206, v1, v238
	v_add_u32_e32 v207, v1, v239
	ds_read_b128 v[132:135], v206 offset:32768
	ds_read_b128 v[136:139], v207 offset:32768
	ds_read_b128 v[140:143], v206 offset:40960
	ds_read_b128 v[144:147], v207 offset:40960
	ds_read_b128 v[148:151], v206 offset:49152
	ds_read_b128 v[152:155], v207 offset:49152
	ds_read_b128 v[156:159], v206 offset:57344
	ds_read_b128 v[160:163], v207 offset:57344
	v_sub_f32_e32 v6, v246, v6
	v_sub_f32_e32 v7, v80, v6
	v_exp_f32_e32 v7, v7
	v_sub_f32_e32 v9, v81, v6
	v_exp_f32_e32 v9, v9
	v_sub_f32_e32 v10, v82, v6
	v_exp_f32_e32 v10, v10
	v_sub_f32_e32 v11, v83, v6
	v_exp_f32_e32 v11, v11
	v_sub_f32_e32 v12, v84, v6
	v_add_f32_e32 v8, 0, v7
	v_exp_f32_e32 v12, v12
	v_sub_f32_e32 v13, v85, v6
	v_add_f32_e32 v8, v9, v8
	v_exp_f32_e32 v13, v13
	v_sub_f32_e32 v14, v86, v6
	v_add_f32_e32 v8, v10, v8
	v_exp_f32_e32 v14, v14
	v_sub_f32_e32 v15, v87, v6
	v_add_f32_e32 v8, v11, v8
	v_exp_f32_e32 v15, v15
	v_sub_f32_e32 v80, v88, v6
	v_add_f32_e32 v8, v12, v8
	v_exp_f32_e32 v80, v80
	v_sub_f32_e32 v81, v89, v6
	v_add_f32_e32 v8, v13, v8
	v_exp_f32_e32 v81, v81
	v_sub_f32_e32 v82, v90, v6
	v_add_f32_e32 v8, v14, v8
	v_exp_f32_e32 v82, v82
	v_sub_f32_e32 v83, v91, v6
	v_add_f32_e32 v8, v15, v8
	v_exp_f32_e32 v83, v83
	v_add_f32_e32 v8, v80, v8
	v_add_f32_e32 v8, v81, v8
	v_sub_f32_e32 v84, v92, v6
	v_sub_f32_e32 v85, v93, v6
	v_sub_f32_e32 v86, v94, v6
	v_sub_f32_e32 v6, v95, v6
	v_add_f32_e32 v8, v82, v8
	v_exp_f32_e32 v87, v6
	v_cvt_pk_bf16_f32 v6, v7, v9
	v_cvt_pk_bf16_f32 v9, v14, v15
	v_add_f32_e32 v8, v83, v8
	v_cvt_pk_bf16_f32 v7, v10, v11
	v_cvt_pk_bf16_f32 v10, v80, v81
	v_cvt_pk_bf16_f32 v11, v82, v83
	v_exp_f32_e32 v84, v84
	v_exp_f32_e32 v85, v85
	v_exp_f32_e32 v86, v86
	v_add_f32_e32 v8, v84, v8
	v_add_f32_e32 v8, v85, v8
	v_add_f32_e32 v8, v86, v8
	v_add_f32_e32 v88, v87, v8
	v_cvt_pk_bf16_f32 v8, v12, v13
	v_cvt_pk_bf16_f32 v12, v84, v85
	v_cvt_pk_bf16_f32 v13, v86, v87
	s_waitcnt lgkmcnt(7)
	v_mfma_f32_32x32x16_bf16 v[64:79], v[132:135], v[6:9], v[64:79]
	v_add_f32_e32 v245, v245, v88
	s_waitcnt lgkmcnt(6)
	v_mfma_f32_32x32x16_bf16 v[64:79], v[136:139], v[10:13], v[64:79]
	s_waitcnt lgkmcnt(5)
	v_mfma_f32_32x32x16_bf16 v[48:63], v[140:143], v[6:9], v[48:63]
	s_waitcnt lgkmcnt(4)
	v_mfma_f32_32x32x16_bf16 v[48:63], v[144:147], v[10:13], v[48:63]
	s_waitcnt lgkmcnt(3)
	v_mfma_f32_32x32x16_bf16 v[32:47], v[148:151], v[6:9], v[32:47]
	s_waitcnt lgkmcnt(2)
	v_mfma_f32_32x32x16_bf16 v[32:47], v[152:155], v[10:13], v[32:47]
	s_waitcnt lgkmcnt(1)
	v_mfma_f32_32x32x16_bf16 v[16:31], v[156:159], v[6:9], v[16:31]
	s_waitcnt lgkmcnt(0)
	v_mfma_f32_32x32x16_bf16 v[16:31], v[160:163], v[10:13], v[16:31]
	s_cmp_ge_u32 s59, s55
	s_cbranch_scc1 .LBB0_308

.LBB0_379:
	v_add_u32_e32 v206, v1, v240
	v_add_u32_e32 v207, v1, v241
	ds_read_b128 v[132:135], v206 offset:32768
	ds_read_b128 v[136:139], v207 offset:32768
	ds_read_b128 v[140:143], v206 offset:40960
	ds_read_b128 v[144:147], v207 offset:40960
	ds_read_b128 v[148:151], v206 offset:49152
	ds_read_b128 v[152:155], v207 offset:49152
	ds_read_b128 v[156:159], v206 offset:57344
	ds_read_b128 v[160:163], v207 offset:57344
	v_sub_f32_e32 v6, v246, v6
	v_sub_f32_e32 v7, v80, v6
	v_exp_f32_e32 v7, v7
	v_sub_f32_e32 v9, v81, v6
	v_exp_f32_e32 v9, v9
	v_sub_f32_e32 v10, v82, v6
	v_exp_f32_e32 v10, v10
	v_sub_f32_e32 v11, v83, v6
	v_exp_f32_e32 v11, v11
	v_sub_f32_e32 v12, v84, v6
	v_add_f32_e32 v8, 0, v7
	v_exp_f32_e32 v12, v12
	v_sub_f32_e32 v13, v85, v6
	v_add_f32_e32 v8, v9, v8
	v_exp_f32_e32 v13, v13
	v_sub_f32_e32 v14, v86, v6
	v_add_f32_e32 v8, v10, v8
	v_exp_f32_e32 v14, v14
	v_sub_f32_e32 v15, v87, v6
	v_add_f32_e32 v8, v11, v8
	v_exp_f32_e32 v15, v15
	v_sub_f32_e32 v80, v88, v6
	v_add_f32_e32 v8, v12, v8
	v_exp_f32_e32 v80, v80
	v_sub_f32_e32 v81, v89, v6
	v_add_f32_e32 v8, v13, v8
	v_exp_f32_e32 v81, v81
	v_sub_f32_e32 v82, v90, v6
	v_add_f32_e32 v8, v14, v8
	v_exp_f32_e32 v82, v82
	v_sub_f32_e32 v83, v91, v6
	v_add_f32_e32 v8, v15, v8
	v_exp_f32_e32 v83, v83
	v_add_f32_e32 v8, v80, v8
	v_add_f32_e32 v8, v81, v8
	v_sub_f32_e32 v84, v92, v6
	v_sub_f32_e32 v85, v93, v6
	v_sub_f32_e32 v86, v94, v6
	v_sub_f32_e32 v6, v95, v6
	v_add_f32_e32 v8, v82, v8
	v_exp_f32_e32 v87, v6
	v_cvt_pk_bf16_f32 v6, v7, v9
	v_cvt_pk_bf16_f32 v9, v14, v15
	v_add_f32_e32 v8, v83, v8
	v_cvt_pk_bf16_f32 v7, v10, v11
	v_cvt_pk_bf16_f32 v10, v80, v81
	v_cvt_pk_bf16_f32 v11, v82, v83
	v_exp_f32_e32 v84, v84
	v_exp_f32_e32 v85, v85
	v_exp_f32_e32 v86, v86
	v_add_f32_e32 v8, v84, v8
	v_add_f32_e32 v8, v85, v8
	v_add_f32_e32 v8, v86, v8
	v_add_f32_e32 v88, v87, v8
	v_cvt_pk_bf16_f32 v8, v12, v13
	v_cvt_pk_bf16_f32 v12, v84, v85
	v_cvt_pk_bf16_f32 v13, v86, v87
	s_waitcnt lgkmcnt(7)
	v_mfma_f32_32x32x16_bf16 v[64:79], v[132:135], v[6:9], v[64:79]
	v_add_f32_e32 v245, v245, v88
	s_waitcnt lgkmcnt(6)
	v_mfma_f32_32x32x16_bf16 v[64:79], v[136:139], v[10:13], v[64:79]
	s_waitcnt lgkmcnt(5)
	v_mfma_f32_32x32x16_bf16 v[48:63], v[140:143], v[6:9], v[48:63]
	s_waitcnt lgkmcnt(4)
	v_mfma_f32_32x32x16_bf16 v[48:63], v[144:147], v[10:13], v[48:63]
	s_waitcnt lgkmcnt(3)
	v_mfma_f32_32x32x16_bf16 v[32:47], v[148:151], v[6:9], v[32:47]
	s_waitcnt lgkmcnt(2)
	v_mfma_f32_32x32x16_bf16 v[32:47], v[152:155], v[10:13], v[32:47]
	s_waitcnt lgkmcnt(1)
	v_mfma_f32_32x32x16_bf16 v[16:31], v[156:159], v[6:9], v[16:31]
	s_waitcnt lgkmcnt(0)
	v_mfma_f32_32x32x16_bf16 v[16:31], v[160:163], v[10:13], v[16:31]
	s_cmp_gt_u32 s59, s55
	s_cbranch_scc1 .LBB0_309
